# same as previous plus wider MFMA-to-VALU hazard pad in attention max block
# baseline (speedup 1.0000x reference)
; DI void attn_unit(LAS unsigned char* lds, const bf16_t* Q, const bf16_t* Kn, const bf16_t* Kpe, const bf16_t* Vt, bf16_t* O, int b, int h, int qb) {
;     ...
;         float mx[2];
; #pragma unroll
;         for (int j = 0; j < 2; ++j) {
;             mx[j] = fmaxf(s[j][0][0], s[j][1][0]);
; #pragma unroll
;             for (int i = 1; i < 16; ++i) mx[j] = fmaxf(mx[j], fmaxf(s[j][0][i], s[j][1][i]));
;         }
;         { const float o0 = __shfl_xor(mx[0], 32), o1 = __shfl_xor(mx[1], 32); mx[0] = fmaxf(mx[0], o0); mx[1] = fmaxf(mx[1], o1); }
.Lat_hmax:
	s_nop 5
	v_max3_f32 v217, v112, v113, v114
	v_max3_f32 v218, v120, v121, v122
	v_max3_f32 v217, v217, v115, v116
	v_max3_f32 v218, v218, v123, v124
	v_max3_f32 v217, v217, v117, v118
	v_max3_f32 v218, v218, v125, v126
	v_max3_f32 v219, v64, v65, v66
	v_max3_f32 v220, v72, v73, v74
	v_max3_f32 v219, v219, v67, v68
	v_max3_f32 v220, v220, v75, v76
	v_max3_f32 v219, v219, v69, v70
	v_max3_f32 v220, v220, v77, v78
	v_max3_f32 v217, v217, v218, v119
	v_max3_f32 v219, v219, v220, v127
	v_max3_f32 v217, v217, v219, v71
	v_max_f32_e32 v217, v79, v217
	v_max3_f32 v218, v96, v97, v98
	v_max3_f32 v219, v104, v105, v106
	v_max3_f32 v218, v218, v99, v100
	v_max3_f32 v219, v219, v107, v108
	v_max3_f32 v218, v218, v101, v102
	v_max3_f32 v219, v219, v109, v110
	v_max3_f32 v220, v80, v81, v82
	v_max3_f32 v221, v88, v89, v90
	v_max3_f32 v220, v220, v83, v84
	v_max3_f32 v221, v221, v91, v92
	v_max3_f32 v220, v220, v85, v86
	v_max3_f32 v221, v221, v93, v94
	v_max3_f32 v218, v218, v219, v103
	v_max3_f32 v220, v220, v221, v111
	v_max3_f32 v218, v218, v220, v87
	v_max_f32_e32 v219, v95, v218
	s_nop 1
	v_permlane32_swap_b32_e32 v217, v219
	v_max_f32_e32 v218, v217, v219
	v_mov_b32_e32 v217, v218
	s_nop 1
	v_permlane32_swap_b32_e32 v218, v217
	v_max_f32_e32 v219, v218, v217
